# pipelined norm row loops: first iteration peeled, steady-state wait relaxed to vmcnt(8) so the previous row's stores are not waited on
# baseline (speedup 1.0000x reference)
.LBB0_107:
	v_and_b32_e32 v1, 0xfc, v162
	v_mov_b32_e32 v19, 0
	s_mov_b32 s0, 0x10200
	v_lshlrev_b32_e32 v158, 2, v1
	v_cmp_gt_i32_e64 s[2:3], s0, v152
	s_mov_b64 s[0:1], exec
	s_nop 0
	v_writelane_b32 v252, s2, 24
	s_nop 1
	v_writelane_b32 v252, s3, 25
	s_and_b64 s[2:3], s[0:1], s[2:3]
	s_mov_b64 exec, s[2:3]
	s_cbranch_execz .LBB0_112
	v_readlane_b32 s22, v252, 4
	v_readlane_b32 s23, v252, 5
	v_readlane_b32 s12, v253, 0
	v_readlane_b32 s13, v253, 1
	v_readlane_b32 s14, v253, 2
	v_readlane_b32 s15, v253, 3
	v_readfirstlane_b32 s16, v152
	s_nop 4
	global_load_dwordx4 v[2:5], v158, s[22:23]
	global_load_dwordx4 v[6:9], v158, s[22:23] offset:1024
	global_load_dwordx4 v[10:13], v158, s[22:23] offset:2048
	global_load_dwordx4 v[14:17], v158, s[22:23] offset:3072
	v_mov_b32_e32 v159, v19
	v_mov_b32_e32 v1, 0x358637bd
	v_mov_b32_e32 v59, 0x3a800000
	v_lshrrev_b32_e32 v20, 1, v158
	s_sub_u32 s17, s16, 0x10000
	s_cmp_gt_u32 s16, 0xffff
	s_cselect_b32 s17, s17, s16
	s_cselect_b32 s18, s14, s12
	s_cselect_b32 s19, s15, s13
	s_lshr_b32 s20, s17, 20
	s_lshl_b32 s17, s17, 12
	s_add_u32 s18, s18, s17
	s_addc_u32 s19, s19, s20
	global_load_dwordx4 v[22:25], v158, s[18:19]
	global_load_dwordx4 v[26:29], v158, s[18:19] offset:1024
	global_load_dwordx4 v[30:33], v158, s[18:19] offset:2048
	global_load_dwordx4 v[34:37], v158, s[18:19] offset:3072
	s_add_u32 s21, s16, s6
	s_cmp_lt_u32 s21, 0x10200
	s_cbranch_scc0 .Lrms0_skip_p
	s_sub_u32 s17, s21, 0x10000
	s_cmp_gt_u32 s21, 0xffff
	s_cselect_b32 s17, s17, s21
	s_cselect_b32 s18, s14, s12
	s_cselect_b32 s19, s15, s13
	s_lshr_b32 s20, s17, 20
	s_lshl_b32 s17, s17, 12
	s_add_u32 s18, s18, s17
	s_addc_u32 s19, s19, s20
	global_load_dwordx4 v[38:41], v158, s[18:19]
	global_load_dwordx4 v[42:45], v158, s[18:19] offset:1024
	global_load_dwordx4 v[46:49], v158, s[18:19] offset:2048
	global_load_dwordx4 v[50:53], v158, s[18:19] offset:3072
	s_waitcnt vmcnt(4)
	s_branch .Lrms0_comp_p

.Lrms0_loop:
	s_add_u32 s21, s16, s6
	s_cmp_lt_u32 s21, 0x10200
	s_cbranch_scc0 .Lrms0_skip_b
	s_sub_u32 s17, s21, 0x10000
	s_cmp_gt_u32 s21, 0xffff
	s_cselect_b32 s17, s17, s21
	s_cselect_b32 s18, s14, s12
	s_cselect_b32 s19, s15, s13
	s_lshr_b32 s20, s17, 20
	s_lshl_b32 s17, s17, 12
	s_add_u32 s18, s18, s17
	s_addc_u32 s19, s19, s20
	global_load_dwordx4 v[22:25], v158, s[18:19]
	global_load_dwordx4 v[26:29], v158, s[18:19] offset:1024
	global_load_dwordx4 v[30:33], v158, s[18:19] offset:2048
	global_load_dwordx4 v[34:37], v158, s[18:19] offset:3072
	s_waitcnt vmcnt(8)
	s_branch .Lrms0_comp_b

.Lrms0_comp_b:
	v_pk_mul_f32 v[54:55], v[38:39], v[38:39]
	v_pk_mul_f32 v[56:57], v[40:41], v[40:41]
	v_pk_fma_f32 v[54:55], v[42:43], v[42:43], v[54:55]
	v_pk_fma_f32 v[56:57], v[44:45], v[44:45], v[56:57]
	v_pk_fma_f32 v[54:55], v[46:47], v[46:47], v[54:55]
	v_pk_fma_f32 v[56:57], v[48:49], v[48:49], v[56:57]
	v_pk_fma_f32 v[54:55], v[50:51], v[50:51], v[54:55]
	v_pk_fma_f32 v[56:57], v[52:53], v[52:53], v[56:57]
	s_nop 0
	v_pk_add_f32 v[54:55], v[54:55], v[56:57]
	s_nop 0
	v_add_f32_e32 v21, v54, v55
	s_nop 1
	v_add_f32_dpp v21, v21, v21 quad_perm:[1,0,3,2] row_mask:0xf bank_mask:0xf bound_ctrl:1
	s_nop 1
	v_add_f32_dpp v21, v21, v21 quad_perm:[2,3,0,1] row_mask:0xf bank_mask:0xf bound_ctrl:1
	s_nop 1
	v_add_f32_dpp v21, v21, v21 row_half_mirror row_mask:0xf bank_mask:0xf bound_ctrl:1
	s_nop 1
	v_add_f32_dpp v21, v21, v21 row_mirror row_mask:0xf bank_mask:0xf bound_ctrl:1
	s_nop 1
	v_mov_b32_dpp v18, v21 row_bcast:15 row_mask:0xa bank_mask:0xf
	v_add_f32_e32 v18, v21, v18
	s_nop 1
	v_mov_b32_dpp v58, v18 row_bcast:31 row_mask:0xc bank_mask:0xf
	v_add_f32_e32 v18, v18, v58
	s_nop 0
	v_readlane_b32 s4, v18, 63
	s_nop 1
	v_fma_f32 v18, s4, v59, v1
	v_rsq_f32_e32 v18, v18
	s_nop 0
	v_mul_f32_e32 v38, v38, v18
	v_mul_f32_e32 v39, v39, v18
	v_mul_f32_e32 v40, v40, v18
	v_mul_f32_e32 v41, v41, v18
	v_mul_f32_e32 v42, v42, v18
	v_mul_f32_e32 v43, v43, v18
	v_mul_f32_e32 v44, v44, v18
	v_mul_f32_e32 v45, v45, v18
	v_mul_f32_e32 v46, v46, v18
	v_mul_f32_e32 v47, v47, v18
	v_mul_f32_e32 v48, v48, v18
	v_mul_f32_e32 v49, v49, v18
	v_mul_f32_e32 v50, v50, v18
	v_mul_f32_e32 v51, v51, v18
	v_mul_f32_e32 v52, v52, v18
	v_mul_f32_e32 v53, v53, v18
	v_mul_f32_e32 v38, v2, v38
	v_mul_f32_e32 v39, v3, v39
	v_mul_f32_e32 v40, v4, v40
	v_mul_f32_e32 v41, v5, v41
	v_mul_f32_e32 v42, v6, v42
	v_mul_f32_e32 v43, v7, v43
	v_mul_f32_e32 v44, v8, v44
	v_mul_f32_e32 v45, v9, v45
	v_mul_f32_e32 v46, v10, v46
	v_mul_f32_e32 v47, v11, v47
	v_mul_f32_e32 v48, v12, v48
	v_mul_f32_e32 v49, v13, v49
	v_mul_f32_e32 v50, v14, v50
	v_mul_f32_e32 v51, v15, v51
	v_mul_f32_e32 v52, v16, v52
	v_mul_f32_e32 v53, v17, v53
	v_cvt_pk_bf16_f32 v38, v38, v39
	v_cvt_pk_bf16_f32 v39, v40, v41
	v_cvt_pk_bf16_f32 v40, v42, v43
	v_cvt_pk_bf16_f32 v41, v44, v45
	v_cvt_pk_bf16_f32 v42, v46, v47
	v_cvt_pk_bf16_f32 v43, v48, v49
	v_cvt_pk_bf16_f32 v44, v50, v51
	v_cvt_pk_bf16_f32 v45, v52, v53
	s_lshl_b32 s24, s16, 11
	s_lshr_b32 s25, s16, 21
	s_add_u32 s24, s94, s24
	s_addc_u32 s25, s95, s25
	global_store_dwordx2 v20, v[38:39], s[24:25]
	global_store_dwordx2 v20, v[40:41], s[24:25] offset:512
	global_store_dwordx2 v20, v[42:43], s[24:25] offset:1024
	global_store_dwordx2 v20, v[44:45], s[24:25] offset:1536
	s_mov_b32 s16, s21
	s_cmp_lt_u32 s16, 0x10200
	s_cbranch_scc0 .LBB0_112
	s_add_u32 s21, s16, s6
	s_cmp_lt_u32 s21, 0x10200
	s_cbranch_scc0 .Lrms0_skip_a
	s_sub_u32 s17, s21, 0x10000
	s_cmp_gt_u32 s21, 0xffff
	s_cselect_b32 s17, s17, s21
	s_cselect_b32 s18, s14, s12
	s_cselect_b32 s19, s15, s13
	s_lshr_b32 s20, s17, 20
	s_lshl_b32 s17, s17, 12
	s_add_u32 s18, s18, s17
	s_addc_u32 s19, s19, s20
	global_load_dwordx4 v[38:41], v158, s[18:19]
	global_load_dwordx4 v[42:45], v158, s[18:19] offset:1024
	global_load_dwordx4 v[46:49], v158, s[18:19] offset:2048
	global_load_dwordx4 v[50:53], v158, s[18:19] offset:3072
	s_waitcnt vmcnt(8)
	s_branch .Lrms0_comp_a

.Lrms0_comp_a:
	v_pk_mul_f32 v[54:55], v[22:23], v[22:23]
	v_pk_mul_f32 v[56:57], v[24:25], v[24:25]
	v_pk_fma_f32 v[54:55], v[26:27], v[26:27], v[54:55]
	v_pk_fma_f32 v[56:57], v[28:29], v[28:29], v[56:57]
	v_pk_fma_f32 v[54:55], v[30:31], v[30:31], v[54:55]
	v_pk_fma_f32 v[56:57], v[32:33], v[32:33], v[56:57]
	v_pk_fma_f32 v[54:55], v[34:35], v[34:35], v[54:55]
	v_pk_fma_f32 v[56:57], v[36:37], v[36:37], v[56:57]
	s_nop 0
	v_pk_add_f32 v[54:55], v[54:55], v[56:57]
	s_nop 0
	v_add_f32_e32 v21, v54, v55
	s_nop 1
	v_add_f32_dpp v21, v21, v21 quad_perm:[1,0,3,2] row_mask:0xf bank_mask:0xf bound_ctrl:1
	s_nop 1
	v_add_f32_dpp v21, v21, v21 quad_perm:[2,3,0,1] row_mask:0xf bank_mask:0xf bound_ctrl:1
	s_nop 1
	v_add_f32_dpp v21, v21, v21 row_half_mirror row_mask:0xf bank_mask:0xf bound_ctrl:1
	s_nop 1
	v_add_f32_dpp v21, v21, v21 row_mirror row_mask:0xf bank_mask:0xf bound_ctrl:1
	s_nop 1
	v_mov_b32_dpp v18, v21 row_bcast:15 row_mask:0xa bank_mask:0xf
	v_add_f32_e32 v18, v21, v18
	s_nop 1
	v_mov_b32_dpp v58, v18 row_bcast:31 row_mask:0xc bank_mask:0xf
	v_add_f32_e32 v18, v18, v58
	s_nop 0
	v_readlane_b32 s4, v18, 63
	s_nop 1
	v_fma_f32 v18, s4, v59, v1
	v_rsq_f32_e32 v18, v18
	s_nop 0
	v_mul_f32_e32 v22, v22, v18
	v_mul_f32_e32 v23, v23, v18
	v_mul_f32_e32 v24, v24, v18
	v_mul_f32_e32 v25, v25, v18
	v_mul_f32_e32 v26, v26, v18
	v_mul_f32_e32 v27, v27, v18
	v_mul_f32_e32 v28, v28, v18
	v_mul_f32_e32 v29, v29, v18
	v_mul_f32_e32 v30, v30, v18
	v_mul_f32_e32 v31, v31, v18
	v_mul_f32_e32 v32, v32, v18
	v_mul_f32_e32 v33, v33, v18
	v_mul_f32_e32 v34, v34, v18
	v_mul_f32_e32 v35, v35, v18
	v_mul_f32_e32 v36, v36, v18
	v_mul_f32_e32 v37, v37, v18
	v_mul_f32_e32 v22, v2, v22
	v_mul_f32_e32 v23, v3, v23
	v_mul_f32_e32 v24, v4, v24
	v_mul_f32_e32 v25, v5, v25
	v_mul_f32_e32 v26, v6, v26
	v_mul_f32_e32 v27, v7, v27
	v_mul_f32_e32 v28, v8, v28
	v_mul_f32_e32 v29, v9, v29
	v_mul_f32_e32 v30, v10, v30
	v_mul_f32_e32 v31, v11, v31
	v_mul_f32_e32 v32, v12, v32
	v_mul_f32_e32 v33, v13, v33
	v_mul_f32_e32 v34, v14, v34
	v_mul_f32_e32 v35, v15, v35
	v_mul_f32_e32 v36, v16, v36
	v_mul_f32_e32 v37, v17, v37
	v_cvt_pk_bf16_f32 v22, v22, v23
	v_cvt_pk_bf16_f32 v23, v24, v25
	v_cvt_pk_bf16_f32 v24, v26, v27
	v_cvt_pk_bf16_f32 v25, v28, v29
	v_cvt_pk_bf16_f32 v26, v30, v31
	v_cvt_pk_bf16_f32 v27, v32, v33
	v_cvt_pk_bf16_f32 v28, v34, v35
	v_cvt_pk_bf16_f32 v29, v36, v37
	s_lshl_b32 s24, s16, 11
	s_lshr_b32 s25, s16, 21
	s_add_u32 s24, s94, s24
	s_addc_u32 s25, s95, s25
	global_store_dwordx2 v20, v[22:23], s[24:25]
	global_store_dwordx2 v20, v[24:25], s[24:25] offset:512
	global_store_dwordx2 v20, v[26:27], s[24:25] offset:1024
	global_store_dwordx2 v20, v[28:29], s[24:25] offset:1536
	s_mov_b32 s16, s21
	s_cmp_lt_u32 s16, 0x10200
	s_cbranch_scc0 .LBB0_112
	s_branch .Lrms0_loop

.LBB0_596:
	s_or_b64 exec, exec, s[4:5]
	s_barrier
	s_mov_b64 s[4:5], exec
	v_readlane_b32 s2, v252, 24
	v_readlane_b32 s3, v252, 25
	s_and_b64 s[2:3], s[4:5], s[2:3]
	s_mov_b64 exec, s[2:3]
	s_cbranch_execz .LBB0_599
	s_waitcnt vmcnt(0)
	v_readlane_b32 s26, v252, 6
	v_readlane_b32 s27, v252, 7
	v_readfirstlane_b32 s16, v152
	s_nop 4
	global_load_dwordx4 v[0:3], v158, s[26:27]
	global_load_dwordx4 v[4:7], v158, s[26:27] offset:1024
	global_load_dwordx4 v[8:11], v158, s[26:27] offset:2048
	global_load_dwordx4 v[12:15], v158, s[26:27] offset:3072
	v_lshrrev_b32_e32 v55, 1, v158
	s_lshl_b32 s17, s16, 12
	s_lshr_b32 s20, s16, 20
	s_add_u32 s18, s92, s17
	s_addc_u32 s19, s93, s20
	global_load_dwordx4 v[16:19], v158, s[18:19]
	global_load_dwordx4 v[20:23], v158, s[18:19] offset:1024
	global_load_dwordx4 v[24:27], v158, s[18:19] offset:2048
	global_load_dwordx4 v[28:31], v158, s[18:19] offset:3072
	s_add_u32 s21, s16, s34
	s_cmp_lt_u32 s21, 0x10200
	s_cbranch_scc0 .Lrms_n0_skip_p
	s_lshl_b32 s17, s21, 12
	s_lshr_b32 s20, s21, 20
	s_add_u32 s18, s92, s17
	s_addc_u32 s19, s93, s20
	global_load_dwordx4 v[32:35], v158, s[18:19]
	global_load_dwordx4 v[36:39], v158, s[18:19] offset:1024
	global_load_dwordx4 v[40:43], v158, s[18:19] offset:2048
	global_load_dwordx4 v[44:47], v158, s[18:19] offset:3072
	s_waitcnt vmcnt(4)
	s_branch .Lrms_n0_comp_p

.Lrms_n0_loop:
	s_add_u32 s21, s16, s34
	s_cmp_lt_u32 s21, 0x10200
	s_cbranch_scc0 .Lrms_n0_skip_b
	s_lshl_b32 s17, s21, 12
	s_lshr_b32 s20, s21, 20
	s_add_u32 s18, s92, s17
	s_addc_u32 s19, s93, s20
	global_load_dwordx4 v[16:19], v158, s[18:19]
	global_load_dwordx4 v[20:23], v158, s[18:19] offset:1024
	global_load_dwordx4 v[24:27], v158, s[18:19] offset:2048
	global_load_dwordx4 v[28:31], v158, s[18:19] offset:3072
	s_waitcnt vmcnt(8)
	s_branch .Lrms_n0_comp_b

.Lrms_n0_comp_b:
	v_pk_mul_f32 v[48:49], v[32:33], v[32:33]
	v_pk_mul_f32 v[50:51], v[34:35], v[34:35]
	v_pk_fma_f32 v[48:49], v[36:37], v[36:37], v[48:49]
	v_pk_fma_f32 v[50:51], v[38:39], v[38:39], v[50:51]
	v_pk_fma_f32 v[48:49], v[40:41], v[40:41], v[48:49]
	v_pk_fma_f32 v[50:51], v[42:43], v[42:43], v[50:51]
	v_pk_fma_f32 v[48:49], v[44:45], v[44:45], v[48:49]
	v_pk_fma_f32 v[50:51], v[46:47], v[46:47], v[50:51]
	s_nop 0
	v_pk_add_f32 v[48:49], v[48:49], v[50:51]
	s_nop 0
	v_add_f32_e32 v52, v48, v49
	s_nop 1
	v_add_f32_dpp v52, v52, v52 quad_perm:[1,0,3,2] row_mask:0xf bank_mask:0xf bound_ctrl:1
	s_nop 1
	v_add_f32_dpp v52, v52, v52 quad_perm:[2,3,0,1] row_mask:0xf bank_mask:0xf bound_ctrl:1
	s_nop 1
	v_add_f32_dpp v52, v52, v52 row_half_mirror row_mask:0xf bank_mask:0xf bound_ctrl:1
	s_nop 1
	v_add_f32_dpp v52, v52, v52 row_mirror row_mask:0xf bank_mask:0xf bound_ctrl:1
	s_nop 1
	v_mov_b32_dpp v53, v52 row_bcast:15 row_mask:0xa bank_mask:0xf
	v_add_f32_e32 v53, v52, v53
	s_nop 1
	v_mov_b32_dpp v54, v53 row_bcast:31 row_mask:0xc bank_mask:0xf
	v_add_f32_e32 v53, v53, v54
	s_nop 0
	v_readlane_b32 s2, v53, 63
	s_nop 1
	v_mov_b32_e32 v53, s2
	v_mul_f32_e32 v53, 0x3a800000, v53
	v_add_f32_e32 v53, 0x358637bd, v53
	v_rsq_f32_e32 v53, v53
	s_nop 0
	v_mul_f32_e32 v32, v32, v53
	v_mul_f32_e32 v33, v33, v53
	v_mul_f32_e32 v34, v34, v53
	v_mul_f32_e32 v35, v35, v53
	v_mul_f32_e32 v36, v36, v53
	v_mul_f32_e32 v37, v37, v53
	v_mul_f32_e32 v38, v38, v53
	v_mul_f32_e32 v39, v39, v53
	v_mul_f32_e32 v40, v40, v53
	v_mul_f32_e32 v41, v41, v53
	v_mul_f32_e32 v42, v42, v53
	v_mul_f32_e32 v43, v43, v53
	v_mul_f32_e32 v44, v44, v53
	v_mul_f32_e32 v45, v45, v53
	v_mul_f32_e32 v46, v46, v53
	v_mul_f32_e32 v47, v47, v53
	v_mul_f32_e32 v32, v0, v32
	v_mul_f32_e32 v33, v1, v33
	v_mul_f32_e32 v34, v2, v34
	v_mul_f32_e32 v35, v3, v35
	v_mul_f32_e32 v36, v4, v36
	v_mul_f32_e32 v37, v5, v37
	v_mul_f32_e32 v38, v6, v38
	v_mul_f32_e32 v39, v7, v39
	v_mul_f32_e32 v40, v8, v40
	v_mul_f32_e32 v41, v9, v41
	v_mul_f32_e32 v42, v10, v42
	v_mul_f32_e32 v43, v11, v43
	v_mul_f32_e32 v44, v12, v44
	v_mul_f32_e32 v45, v13, v45
	v_mul_f32_e32 v46, v14, v46
	v_mul_f32_e32 v47, v15, v47
	v_cvt_pk_bf16_f32 v32, v32, v33
	v_cvt_pk_bf16_f32 v33, v34, v35
	v_cvt_pk_bf16_f32 v34, v36, v37
	v_cvt_pk_bf16_f32 v35, v38, v39
	v_cvt_pk_bf16_f32 v36, v40, v41
	v_cvt_pk_bf16_f32 v37, v42, v43
	v_cvt_pk_bf16_f32 v38, v44, v45
	v_cvt_pk_bf16_f32 v39, v46, v47
	s_lshl_b32 s24, s16, 11
	s_lshr_b32 s25, s16, 21
	s_add_u32 s24, s94, s24
	s_addc_u32 s25, s95, s25
	global_store_dwordx2 v55, v[32:33], s[24:25]
	global_store_dwordx2 v55, v[34:35], s[24:25] offset:512
	global_store_dwordx2 v55, v[36:37], s[24:25] offset:1024
	global_store_dwordx2 v55, v[38:39], s[24:25] offset:1536
	s_mov_b32 s16, s21
	s_cmp_lt_u32 s16, 0x10200
	s_cbranch_scc0 .LBB0_599
	s_add_u32 s21, s16, s34
	s_cmp_lt_u32 s21, 0x10200
	s_cbranch_scc0 .Lrms_n0_skip_a
	s_lshl_b32 s17, s21, 12
	s_lshr_b32 s20, s21, 20
	s_add_u32 s18, s92, s17
	s_addc_u32 s19, s93, s20
	global_load_dwordx4 v[32:35], v158, s[18:19]
	global_load_dwordx4 v[36:39], v158, s[18:19] offset:1024
	global_load_dwordx4 v[40:43], v158, s[18:19] offset:2048
	global_load_dwordx4 v[44:47], v158, s[18:19] offset:3072
	s_waitcnt vmcnt(8)
	s_branch .Lrms_n0_comp_a

.Lrms_n0_comp_a:
	v_pk_mul_f32 v[48:49], v[16:17], v[16:17]
	v_pk_mul_f32 v[50:51], v[18:19], v[18:19]
	v_pk_fma_f32 v[48:49], v[20:21], v[20:21], v[48:49]
	v_pk_fma_f32 v[50:51], v[22:23], v[22:23], v[50:51]
	v_pk_fma_f32 v[48:49], v[24:25], v[24:25], v[48:49]
	v_pk_fma_f32 v[50:51], v[26:27], v[26:27], v[50:51]
	v_pk_fma_f32 v[48:49], v[28:29], v[28:29], v[48:49]
	v_pk_fma_f32 v[50:51], v[30:31], v[30:31], v[50:51]
	s_nop 0
	v_pk_add_f32 v[48:49], v[48:49], v[50:51]
	s_nop 0
	v_add_f32_e32 v52, v48, v49
	s_nop 1
	v_add_f32_dpp v52, v52, v52 quad_perm:[1,0,3,2] row_mask:0xf bank_mask:0xf bound_ctrl:1
	s_nop 1
	v_add_f32_dpp v52, v52, v52 quad_perm:[2,3,0,1] row_mask:0xf bank_mask:0xf bound_ctrl:1
	s_nop 1
	v_add_f32_dpp v52, v52, v52 row_half_mirror row_mask:0xf bank_mask:0xf bound_ctrl:1
	s_nop 1
	v_add_f32_dpp v52, v52, v52 row_mirror row_mask:0xf bank_mask:0xf bound_ctrl:1
	s_nop 1
	v_mov_b32_dpp v53, v52 row_bcast:15 row_mask:0xa bank_mask:0xf
	v_add_f32_e32 v53, v52, v53
	s_nop 1
	v_mov_b32_dpp v54, v53 row_bcast:31 row_mask:0xc bank_mask:0xf
	v_add_f32_e32 v53, v53, v54
	s_nop 0
	v_readlane_b32 s2, v53, 63
	s_nop 1
	v_mov_b32_e32 v53, s2
	v_mul_f32_e32 v53, 0x3a800000, v53
	v_add_f32_e32 v53, 0x358637bd, v53
	v_rsq_f32_e32 v53, v53
	s_nop 0
	v_mul_f32_e32 v16, v16, v53
	v_mul_f32_e32 v17, v17, v53
	v_mul_f32_e32 v18, v18, v53
	v_mul_f32_e32 v19, v19, v53
	v_mul_f32_e32 v20, v20, v53
	v_mul_f32_e32 v21, v21, v53
	v_mul_f32_e32 v22, v22, v53
	v_mul_f32_e32 v23, v23, v53
	v_mul_f32_e32 v24, v24, v53
	v_mul_f32_e32 v25, v25, v53
	v_mul_f32_e32 v26, v26, v53
	v_mul_f32_e32 v27, v27, v53
	v_mul_f32_e32 v28, v28, v53
	v_mul_f32_e32 v29, v29, v53
	v_mul_f32_e32 v30, v30, v53
	v_mul_f32_e32 v31, v31, v53
	v_mul_f32_e32 v16, v0, v16
	v_mul_f32_e32 v17, v1, v17
	v_mul_f32_e32 v18, v2, v18
	v_mul_f32_e32 v19, v3, v19
	v_mul_f32_e32 v20, v4, v20
	v_mul_f32_e32 v21, v5, v21
	v_mul_f32_e32 v22, v6, v22
	v_mul_f32_e32 v23, v7, v23
	v_mul_f32_e32 v24, v8, v24
	v_mul_f32_e32 v25, v9, v25
	v_mul_f32_e32 v26, v10, v26
	v_mul_f32_e32 v27, v11, v27
	v_mul_f32_e32 v28, v12, v28
	v_mul_f32_e32 v29, v13, v29
	v_mul_f32_e32 v30, v14, v30
	v_mul_f32_e32 v31, v15, v31
	v_cvt_pk_bf16_f32 v16, v16, v17
	v_cvt_pk_bf16_f32 v17, v18, v19
	v_cvt_pk_bf16_f32 v18, v20, v21
	v_cvt_pk_bf16_f32 v19, v22, v23
	v_cvt_pk_bf16_f32 v20, v24, v25
	v_cvt_pk_bf16_f32 v21, v26, v27
	v_cvt_pk_bf16_f32 v22, v28, v29
	v_cvt_pk_bf16_f32 v23, v30, v31
	s_lshl_b32 s24, s16, 11
	s_lshr_b32 s25, s16, 21
	s_add_u32 s24, s94, s24
	s_addc_u32 s25, s95, s25
	global_store_dwordx2 v55, v[16:17], s[24:25]
	global_store_dwordx2 v55, v[18:19], s[24:25] offset:512
	global_store_dwordx2 v55, v[20:21], s[24:25] offset:1024
	global_store_dwordx2 v55, v[22:23], s[24:25] offset:1536
	s_mov_b32 s16, s21
	s_cmp_lt_u32 s16, 0x10200
	s_cbranch_scc0 .LBB0_599
	s_branch .Lrms_n0_loop

.LBB0_1058:
	s_or_b64 exec, exec, s[2:3]
	s_barrier
	s_mov_b64 s[2:3], exec
	v_readlane_b32 s4, v252, 24
	v_readlane_b32 s5, v252, 25
	s_and_b64 s[4:5], s[2:3], s[4:5]
	s_mov_b64 exec, s[4:5]
	s_cbranch_execz .LBB0_1061
	s_waitcnt vmcnt(0)
	v_readlane_b32 s80, v252, 6
	v_readlane_b32 s81, v252, 7
	v_readfirstlane_b32 s72, v152
	s_nop 4
	s_add_u32 s80, s80, 0x1000
	s_addc_u32 s81, s81, 0
	global_load_dwordx4 v[0:3], v158, s[80:81]
	global_load_dwordx4 v[4:7], v158, s[80:81] offset:1024
	global_load_dwordx4 v[8:11], v158, s[80:81] offset:2048
	global_load_dwordx4 v[12:15], v158, s[80:81] offset:3072
	v_lshrrev_b32_e32 v55, 1, v158
	v_mov_b32_e32 v159, 0
	s_lshl_b32 s73, s72, 12
	s_lshr_b32 s76, s72, 20
	s_add_u32 s74, s92, s73
	s_addc_u32 s75, s93, s76
	global_load_dwordx4 v[16:19], v158, s[74:75]
	global_load_dwordx4 v[20:23], v158, s[74:75] offset:1024
	global_load_dwordx4 v[24:27], v158, s[74:75] offset:2048
	global_load_dwordx4 v[28:31], v158, s[74:75] offset:3072
	s_add_u32 s77, s72, s34
	s_cmp_lt_u32 s77, 0x10200
	s_cbranch_scc0 .Lrms_n1_skip_p
	s_lshl_b32 s73, s77, 12
	s_lshr_b32 s76, s77, 20
	s_add_u32 s74, s92, s73
	s_addc_u32 s75, s93, s76
	global_load_dwordx4 v[32:35], v158, s[74:75]
	global_load_dwordx4 v[36:39], v158, s[74:75] offset:1024
	global_load_dwordx4 v[40:43], v158, s[74:75] offset:2048
	global_load_dwordx4 v[44:47], v158, s[74:75] offset:3072
	s_waitcnt vmcnt(4)
	s_branch .Lrms_n1_comp_p

.Lrms_n1_loop:
	s_add_u32 s77, s72, s34
	s_cmp_lt_u32 s77, 0x10200
	s_cbranch_scc0 .Lrms_n1_skip_b
	s_lshl_b32 s73, s77, 12
	s_lshr_b32 s76, s77, 20
	s_add_u32 s74, s92, s73
	s_addc_u32 s75, s93, s76
	global_load_dwordx4 v[16:19], v158, s[74:75]
	global_load_dwordx4 v[20:23], v158, s[74:75] offset:1024
	global_load_dwordx4 v[24:27], v158, s[74:75] offset:2048
	global_load_dwordx4 v[28:31], v158, s[74:75] offset:3072
	s_waitcnt vmcnt(8)
	s_branch .Lrms_n1_comp_b

.Lrms_n1_comp_b:
	v_pk_mul_f32 v[48:49], v[32:33], v[32:33]
	v_pk_mul_f32 v[50:51], v[34:35], v[34:35]
	v_pk_fma_f32 v[48:49], v[36:37], v[36:37], v[48:49]
	v_pk_fma_f32 v[50:51], v[38:39], v[38:39], v[50:51]
	v_pk_fma_f32 v[48:49], v[40:41], v[40:41], v[48:49]
	v_pk_fma_f32 v[50:51], v[42:43], v[42:43], v[50:51]
	v_pk_fma_f32 v[48:49], v[44:45], v[44:45], v[48:49]
	v_pk_fma_f32 v[50:51], v[46:47], v[46:47], v[50:51]
	s_nop 0
	v_pk_add_f32 v[48:49], v[48:49], v[50:51]
	s_nop 0
	v_add_f32_e32 v52, v48, v49
	s_nop 1
	v_add_f32_dpp v52, v52, v52 quad_perm:[1,0,3,2] row_mask:0xf bank_mask:0xf bound_ctrl:1
	s_nop 1
	v_add_f32_dpp v52, v52, v52 quad_perm:[2,3,0,1] row_mask:0xf bank_mask:0xf bound_ctrl:1
	s_nop 1
	v_add_f32_dpp v52, v52, v52 row_half_mirror row_mask:0xf bank_mask:0xf bound_ctrl:1
	s_nop 1
	v_add_f32_dpp v52, v52, v52 row_mirror row_mask:0xf bank_mask:0xf bound_ctrl:1
	s_nop 1
	v_mov_b32_dpp v53, v52 row_bcast:15 row_mask:0xa bank_mask:0xf
	v_add_f32_e32 v53, v52, v53
	s_nop 1
	v_mov_b32_dpp v54, v53 row_bcast:31 row_mask:0xc bank_mask:0xf
	v_add_f32_e32 v53, v53, v54
	s_nop 0
	v_readlane_b32 s4, v53, 63
	s_nop 1
	v_mov_b32_e32 v53, s4
	v_mul_f32_e32 v53, 0x3a800000, v53
	v_add_f32_e32 v53, 0x358637bd, v53
	v_rsq_f32_e32 v53, v53
	s_nop 0
	v_mul_f32_e32 v32, v32, v53
	v_mul_f32_e32 v33, v33, v53
	v_mul_f32_e32 v34, v34, v53
	v_mul_f32_e32 v35, v35, v53
	v_mul_f32_e32 v36, v36, v53
	v_mul_f32_e32 v37, v37, v53
	v_mul_f32_e32 v38, v38, v53
	v_mul_f32_e32 v39, v39, v53
	v_mul_f32_e32 v40, v40, v53
	v_mul_f32_e32 v41, v41, v53
	v_mul_f32_e32 v42, v42, v53
	v_mul_f32_e32 v43, v43, v53
	v_mul_f32_e32 v44, v44, v53
	v_mul_f32_e32 v45, v45, v53
	v_mul_f32_e32 v46, v46, v53
	v_mul_f32_e32 v47, v47, v53
	v_mul_f32_e32 v32, v0, v32
	v_mul_f32_e32 v33, v1, v33
	v_mul_f32_e32 v34, v2, v34
	v_mul_f32_e32 v35, v3, v35
	v_mul_f32_e32 v36, v4, v36
	v_mul_f32_e32 v37, v5, v37
	v_mul_f32_e32 v38, v6, v38
	v_mul_f32_e32 v39, v7, v39
	v_mul_f32_e32 v40, v8, v40
	v_mul_f32_e32 v41, v9, v41
	v_mul_f32_e32 v42, v10, v42
	v_mul_f32_e32 v43, v11, v43
	v_mul_f32_e32 v44, v12, v44
	v_mul_f32_e32 v45, v13, v45
	v_mul_f32_e32 v46, v14, v46
	v_mul_f32_e32 v47, v15, v47
	v_cvt_pk_bf16_f32 v32, v32, v33
	v_cvt_pk_bf16_f32 v33, v34, v35
	v_cvt_pk_bf16_f32 v34, v36, v37
	v_cvt_pk_bf16_f32 v35, v38, v39
	v_cvt_pk_bf16_f32 v36, v40, v41
	v_cvt_pk_bf16_f32 v37, v42, v43
	v_cvt_pk_bf16_f32 v38, v44, v45
	v_cvt_pk_bf16_f32 v39, v46, v47
	s_lshl_b32 s78, s72, 11
	s_lshr_b32 s79, s72, 21
	s_add_u32 s78, s94, s78
	s_addc_u32 s79, s95, s79
	global_store_dwordx2 v55, v[32:33], s[78:79]
	global_store_dwordx2 v55, v[34:35], s[78:79] offset:512
	global_store_dwordx2 v55, v[36:37], s[78:79] offset:1024
	global_store_dwordx2 v55, v[38:39], s[78:79] offset:1536
	s_mov_b32 s72, s77
	s_cmp_lt_u32 s72, 0x10200
	s_cbranch_scc0 .LBB0_1061
	s_add_u32 s77, s72, s34
	s_cmp_lt_u32 s77, 0x10200
	s_cbranch_scc0 .Lrms_n1_skip_a
	s_lshl_b32 s73, s77, 12
	s_lshr_b32 s76, s77, 20
	s_add_u32 s74, s92, s73
	s_addc_u32 s75, s93, s76
	global_load_dwordx4 v[32:35], v158, s[74:75]
	global_load_dwordx4 v[36:39], v158, s[74:75] offset:1024
	global_load_dwordx4 v[40:43], v158, s[74:75] offset:2048
	global_load_dwordx4 v[44:47], v158, s[74:75] offset:3072
	s_waitcnt vmcnt(8)
	s_branch .Lrms_n1_comp_a

.Lrms_n1_comp_a:
	v_pk_mul_f32 v[48:49], v[16:17], v[16:17]
	v_pk_mul_f32 v[50:51], v[18:19], v[18:19]
	v_pk_fma_f32 v[48:49], v[20:21], v[20:21], v[48:49]
	v_pk_fma_f32 v[50:51], v[22:23], v[22:23], v[50:51]
	v_pk_fma_f32 v[48:49], v[24:25], v[24:25], v[48:49]
	v_pk_fma_f32 v[50:51], v[26:27], v[26:27], v[50:51]
	v_pk_fma_f32 v[48:49], v[28:29], v[28:29], v[48:49]
	v_pk_fma_f32 v[50:51], v[30:31], v[30:31], v[50:51]
	s_nop 0
	v_pk_add_f32 v[48:49], v[48:49], v[50:51]
	s_nop 0
	v_add_f32_e32 v52, v48, v49
	s_nop 1
	v_add_f32_dpp v52, v52, v52 quad_perm:[1,0,3,2] row_mask:0xf bank_mask:0xf bound_ctrl:1
	s_nop 1
	v_add_f32_dpp v52, v52, v52 quad_perm:[2,3,0,1] row_mask:0xf bank_mask:0xf bound_ctrl:1
	s_nop 1
	v_add_f32_dpp v52, v52, v52 row_half_mirror row_mask:0xf bank_mask:0xf bound_ctrl:1
	s_nop 1
	v_add_f32_dpp v52, v52, v52 row_mirror row_mask:0xf bank_mask:0xf bound_ctrl:1
	s_nop 1
	v_mov_b32_dpp v53, v52 row_bcast:15 row_mask:0xa bank_mask:0xf
	v_add_f32_e32 v53, v52, v53
	s_nop 1
	v_mov_b32_dpp v54, v53 row_bcast:31 row_mask:0xc bank_mask:0xf
	v_add_f32_e32 v53, v53, v54
	s_nop 0
	v_readlane_b32 s4, v53, 63
	s_nop 1
	v_mov_b32_e32 v53, s4
	v_mul_f32_e32 v53, 0x3a800000, v53
	v_add_f32_e32 v53, 0x358637bd, v53
	v_rsq_f32_e32 v53, v53
	s_nop 0
	v_mul_f32_e32 v16, v16, v53
	v_mul_f32_e32 v17, v17, v53
	v_mul_f32_e32 v18, v18, v53
	v_mul_f32_e32 v19, v19, v53
	v_mul_f32_e32 v20, v20, v53
	v_mul_f32_e32 v21, v21, v53
	v_mul_f32_e32 v22, v22, v53
	v_mul_f32_e32 v23, v23, v53
	v_mul_f32_e32 v24, v24, v53
	v_mul_f32_e32 v25, v25, v53
	v_mul_f32_e32 v26, v26, v53
	v_mul_f32_e32 v27, v27, v53
	v_mul_f32_e32 v28, v28, v53
	v_mul_f32_e32 v29, v29, v53
	v_mul_f32_e32 v30, v30, v53
	v_mul_f32_e32 v31, v31, v53
	v_mul_f32_e32 v16, v0, v16
	v_mul_f32_e32 v17, v1, v17
	v_mul_f32_e32 v18, v2, v18
	v_mul_f32_e32 v19, v3, v19
	v_mul_f32_e32 v20, v4, v20
	v_mul_f32_e32 v21, v5, v21
	v_mul_f32_e32 v22, v6, v22
	v_mul_f32_e32 v23, v7, v23
	v_mul_f32_e32 v24, v8, v24
	v_mul_f32_e32 v25, v9, v25
	v_mul_f32_e32 v26, v10, v26
	v_mul_f32_e32 v27, v11, v27
	v_mul_f32_e32 v28, v12, v28
	v_mul_f32_e32 v29, v13, v29
	v_mul_f32_e32 v30, v14, v30
	v_mul_f32_e32 v31, v15, v31
	v_cvt_pk_bf16_f32 v16, v16, v17
	v_cvt_pk_bf16_f32 v17, v18, v19
	v_cvt_pk_bf16_f32 v18, v20, v21
	v_cvt_pk_bf16_f32 v19, v22, v23
	v_cvt_pk_bf16_f32 v20, v24, v25
	v_cvt_pk_bf16_f32 v21, v26, v27
	v_cvt_pk_bf16_f32 v22, v28, v29
	v_cvt_pk_bf16_f32 v23, v30, v31
	s_lshl_b32 s78, s72, 11
	s_lshr_b32 s79, s72, 21
	s_add_u32 s78, s94, s78
	s_addc_u32 s79, s95, s79
	global_store_dwordx2 v55, v[16:17], s[78:79]
	global_store_dwordx2 v55, v[18:19], s[78:79] offset:512
	global_store_dwordx2 v55, v[20:21], s[78:79] offset:1024
	global_store_dwordx2 v55, v[22:23], s[78:79] offset:1536
	s_mov_b32 s72, s77
	s_cmp_lt_u32 s72, 0x10200
	s_cbranch_scc0 .LBB0_1061
	s_branch .Lrms_n1_loop
